# s5_prompt: 8-token ILP x-phase + scalar-fma recurrence, pass-2 y=Re(C h) via v_mfma_f32_16x16x4_f32 (f32); tile-start barrier in GU/INM cores
# speedup vs baseline: 1.1027x; 1.0314x over previous
.LBB0_464:
	s_or_b64 exec, exec, s[4:5]
	s_mov_b32 s4, 0
	v_mov_b32_e32 v53, s8
	ds_read_b128 v[132:135], v53 offset:0
	ds_read_b128 v[136:139], v53 offset:64
	ds_read_b128 v[140:143], v53 offset:128
	ds_read_b128 v[144:147], v53 offset:192
	ds_read_b128 v[148:151], v53 offset:256
	ds_read_b128 v[152:155], v53 offset:320
	ds_read_b128 v[156:159], v53 offset:384
	ds_read_b128 v[160:163], v53 offset:448
	ds_read_b128 v[164:167], v53 offset:16
	ds_read_b128 v[168:171], v53 offset:80
	ds_read_b128 v[172:175], v53 offset:144
	ds_read_b128 v[176:179], v53 offset:208
	ds_read_b128 v[180:183], v53 offset:272
	ds_read_b128 v[184:187], v53 offset:336
	ds_read_b128 v[188:191], v53 offset:400
	ds_read_b128 v[192:195], v53 offset:464
	s_waitcnt lgkmcnt(8)
	v_pk_fma_f32 v[84:85], v[36:37], v[132:133], 0 op_sel_hi:[1,0,0]
	v_pk_fma_f32 v[86:87], v[36:37], v[136:137], 0 op_sel_hi:[1,0,0]
	v_pk_fma_f32 v[88:89], v[36:37], v[140:141], 0 op_sel_hi:[1,0,0]
	v_pk_fma_f32 v[90:91], v[36:37], v[144:145], 0 op_sel_hi:[1,0,0]
	v_pk_fma_f32 v[92:93], v[36:37], v[148:149], 0 op_sel_hi:[1,0,0]
	v_pk_fma_f32 v[94:95], v[36:37], v[152:153], 0 op_sel_hi:[1,0,0]
	v_pk_fma_f32 v[96:97], v[36:37], v[156:157], 0 op_sel_hi:[1,0,0]
	v_pk_fma_f32 v[98:99], v[36:37], v[160:161], 0 op_sel_hi:[1,0,0]
	v_pk_fma_f32 v[84:85], v[28:29], v[132:133], v[84:85] op_sel:[0,1,0]
	v_pk_fma_f32 v[86:87], v[28:29], v[136:137], v[86:87] op_sel:[0,1,0]
	v_pk_fma_f32 v[88:89], v[28:29], v[140:141], v[88:89] op_sel:[0,1,0]
	v_pk_fma_f32 v[90:91], v[28:29], v[144:145], v[90:91] op_sel:[0,1,0]
	v_pk_fma_f32 v[92:93], v[28:29], v[148:149], v[92:93] op_sel:[0,1,0]
	v_pk_fma_f32 v[94:95], v[28:29], v[152:153], v[94:95] op_sel:[0,1,0]
	v_pk_fma_f32 v[96:97], v[28:29], v[156:157], v[96:97] op_sel:[0,1,0]
	v_pk_fma_f32 v[98:99], v[28:29], v[160:161], v[98:99] op_sel:[0,1,0]
	v_pk_fma_f32 v[84:85], v[24:25], v[134:135], v[84:85] op_sel_hi:[1,0,1]
	v_pk_fma_f32 v[86:87], v[24:25], v[138:139], v[86:87] op_sel_hi:[1,0,1]
	v_pk_fma_f32 v[88:89], v[24:25], v[142:143], v[88:89] op_sel_hi:[1,0,1]
	v_pk_fma_f32 v[90:91], v[24:25], v[146:147], v[90:91] op_sel_hi:[1,0,1]
	v_pk_fma_f32 v[92:93], v[24:25], v[150:151], v[92:93] op_sel_hi:[1,0,1]
	v_pk_fma_f32 v[94:95], v[24:25], v[154:155], v[94:95] op_sel_hi:[1,0,1]
	v_pk_fma_f32 v[96:97], v[24:25], v[158:159], v[96:97] op_sel_hi:[1,0,1]
	v_pk_fma_f32 v[98:99], v[24:25], v[162:163], v[98:99] op_sel_hi:[1,0,1]
	v_pk_fma_f32 v[84:85], v[26:27], v[134:135], v[84:85] op_sel:[0,1,0]
	v_pk_fma_f32 v[86:87], v[26:27], v[138:139], v[86:87] op_sel:[0,1,0]
	v_pk_fma_f32 v[88:89], v[26:27], v[142:143], v[88:89] op_sel:[0,1,0]
	v_pk_fma_f32 v[90:91], v[26:27], v[146:147], v[90:91] op_sel:[0,1,0]
	v_pk_fma_f32 v[92:93], v[26:27], v[150:151], v[92:93] op_sel:[0,1,0]
	v_pk_fma_f32 v[94:95], v[26:27], v[154:155], v[94:95] op_sel:[0,1,0]
	v_pk_fma_f32 v[96:97], v[26:27], v[158:159], v[96:97] op_sel:[0,1,0]
	v_pk_fma_f32 v[98:99], v[26:27], v[162:163], v[98:99] op_sel:[0,1,0]
	ds_read_b128 v[132:135], v53 offset:32
	ds_read_b128 v[136:139], v53 offset:96
	ds_read_b128 v[140:143], v53 offset:160
	ds_read_b128 v[144:147], v53 offset:224
	ds_read_b128 v[148:151], v53 offset:288
	ds_read_b128 v[152:155], v53 offset:352
	ds_read_b128 v[156:159], v53 offset:416
	ds_read_b128 v[160:163], v53 offset:480
	s_waitcnt lgkmcnt(8)
	v_pk_fma_f32 v[84:85], v[30:31], v[164:165], v[84:85] op_sel_hi:[1,0,1]
	v_pk_fma_f32 v[86:87], v[30:31], v[168:169], v[86:87] op_sel_hi:[1,0,1]
	v_pk_fma_f32 v[88:89], v[30:31], v[172:173], v[88:89] op_sel_hi:[1,0,1]
	v_pk_fma_f32 v[90:91], v[30:31], v[176:177], v[90:91] op_sel_hi:[1,0,1]
	v_pk_fma_f32 v[92:93], v[30:31], v[180:181], v[92:93] op_sel_hi:[1,0,1]
	v_pk_fma_f32 v[94:95], v[30:31], v[184:185], v[94:95] op_sel_hi:[1,0,1]
	v_pk_fma_f32 v[96:97], v[30:31], v[188:189], v[96:97] op_sel_hi:[1,0,1]
	v_pk_fma_f32 v[98:99], v[30:31], v[192:193], v[98:99] op_sel_hi:[1,0,1]
	v_pk_fma_f32 v[84:85], v[16:17], v[164:165], v[84:85] op_sel:[0,1,0]
	v_pk_fma_f32 v[86:87], v[16:17], v[168:169], v[86:87] op_sel:[0,1,0]
	v_pk_fma_f32 v[88:89], v[16:17], v[172:173], v[88:89] op_sel:[0,1,0]
	v_pk_fma_f32 v[90:91], v[16:17], v[176:177], v[90:91] op_sel:[0,1,0]
	v_pk_fma_f32 v[92:93], v[16:17], v[180:181], v[92:93] op_sel:[0,1,0]
	v_pk_fma_f32 v[94:95], v[16:17], v[184:185], v[94:95] op_sel:[0,1,0]
	v_pk_fma_f32 v[96:97], v[16:17], v[188:189], v[96:97] op_sel:[0,1,0]
	v_pk_fma_f32 v[98:99], v[16:17], v[192:193], v[98:99] op_sel:[0,1,0]
	v_pk_fma_f32 v[84:85], v[20:21], v[166:167], v[84:85] op_sel_hi:[1,0,1]
	v_pk_fma_f32 v[86:87], v[20:21], v[170:171], v[86:87] op_sel_hi:[1,0,1]
	v_pk_fma_f32 v[88:89], v[20:21], v[174:175], v[88:89] op_sel_hi:[1,0,1]
	v_pk_fma_f32 v[90:91], v[20:21], v[178:179], v[90:91] op_sel_hi:[1,0,1]
	v_pk_fma_f32 v[92:93], v[20:21], v[182:183], v[92:93] op_sel_hi:[1,0,1]
	v_pk_fma_f32 v[94:95], v[20:21], v[186:187], v[94:95] op_sel_hi:[1,0,1]
	v_pk_fma_f32 v[96:97], v[20:21], v[190:191], v[96:97] op_sel_hi:[1,0,1]
	v_pk_fma_f32 v[98:99], v[20:21], v[194:195], v[98:99] op_sel_hi:[1,0,1]
	v_pk_fma_f32 v[84:85], v[18:19], v[166:167], v[84:85] op_sel:[0,1,0]
	v_pk_fma_f32 v[86:87], v[18:19], v[170:171], v[86:87] op_sel:[0,1,0]
	v_pk_fma_f32 v[88:89], v[18:19], v[174:175], v[88:89] op_sel:[0,1,0]
	v_pk_fma_f32 v[90:91], v[18:19], v[178:179], v[90:91] op_sel:[0,1,0]
	v_pk_fma_f32 v[92:93], v[18:19], v[182:183], v[92:93] op_sel:[0,1,0]
	v_pk_fma_f32 v[94:95], v[18:19], v[186:187], v[94:95] op_sel:[0,1,0]
	v_pk_fma_f32 v[96:97], v[18:19], v[190:191], v[96:97] op_sel:[0,1,0]
	v_pk_fma_f32 v[98:99], v[18:19], v[194:195], v[98:99] op_sel:[0,1,0]
	ds_read_b128 v[164:167], v53 offset:48
	ds_read_b128 v[168:171], v53 offset:112
	ds_read_b128 v[172:175], v53 offset:176
	ds_read_b128 v[176:179], v53 offset:240
	ds_read_b128 v[180:183], v53 offset:304
	ds_read_b128 v[184:187], v53 offset:368
	ds_read_b128 v[188:191], v53 offset:432
	ds_read_b128 v[192:195], v53 offset:496
	s_waitcnt lgkmcnt(8)
	v_pk_fma_f32 v[84:85], v[22:23], v[132:133], v[84:85] op_sel_hi:[1,0,1]
	v_pk_fma_f32 v[86:87], v[22:23], v[136:137], v[86:87] op_sel_hi:[1,0,1]
	v_pk_fma_f32 v[88:89], v[22:23], v[140:141], v[88:89] op_sel_hi:[1,0,1]
	v_pk_fma_f32 v[90:91], v[22:23], v[144:145], v[90:91] op_sel_hi:[1,0,1]
	v_pk_fma_f32 v[92:93], v[22:23], v[148:149], v[92:93] op_sel_hi:[1,0,1]
	v_pk_fma_f32 v[94:95], v[22:23], v[152:153], v[94:95] op_sel_hi:[1,0,1]
	v_pk_fma_f32 v[96:97], v[22:23], v[156:157], v[96:97] op_sel_hi:[1,0,1]
	v_pk_fma_f32 v[98:99], v[22:23], v[160:161], v[98:99] op_sel_hi:[1,0,1]
	v_pk_fma_f32 v[84:85], v[8:9], v[132:133], v[84:85] op_sel:[0,1,0]
	v_pk_fma_f32 v[86:87], v[8:9], v[136:137], v[86:87] op_sel:[0,1,0]
	v_pk_fma_f32 v[88:89], v[8:9], v[140:141], v[88:89] op_sel:[0,1,0]
	v_pk_fma_f32 v[90:91], v[8:9], v[144:145], v[90:91] op_sel:[0,1,0]
	v_pk_fma_f32 v[92:93], v[8:9], v[148:149], v[92:93] op_sel:[0,1,0]
	v_pk_fma_f32 v[94:95], v[8:9], v[152:153], v[94:95] op_sel:[0,1,0]
	v_pk_fma_f32 v[96:97], v[8:9], v[156:157], v[96:97] op_sel:[0,1,0]
	v_pk_fma_f32 v[98:99], v[8:9], v[160:161], v[98:99] op_sel:[0,1,0]
	v_pk_fma_f32 v[84:85], v[12:13], v[134:135], v[84:85] op_sel_hi:[1,0,1]
	v_pk_fma_f32 v[86:87], v[12:13], v[138:139], v[86:87] op_sel_hi:[1,0,1]
	v_pk_fma_f32 v[88:89], v[12:13], v[142:143], v[88:89] op_sel_hi:[1,0,1]
	v_pk_fma_f32 v[90:91], v[12:13], v[146:147], v[90:91] op_sel_hi:[1,0,1]
	v_pk_fma_f32 v[92:93], v[12:13], v[150:151], v[92:93] op_sel_hi:[1,0,1]
	v_pk_fma_f32 v[94:95], v[12:13], v[154:155], v[94:95] op_sel_hi:[1,0,1]
	v_pk_fma_f32 v[96:97], v[12:13], v[158:159], v[96:97] op_sel_hi:[1,0,1]
	v_pk_fma_f32 v[98:99], v[12:13], v[162:163], v[98:99] op_sel_hi:[1,0,1]
	v_pk_fma_f32 v[84:85], v[10:11], v[134:135], v[84:85] op_sel:[0,1,0]
	v_pk_fma_f32 v[86:87], v[10:11], v[138:139], v[86:87] op_sel:[0,1,0]
	v_pk_fma_f32 v[88:89], v[10:11], v[142:143], v[88:89] op_sel:[0,1,0]
	v_pk_fma_f32 v[90:91], v[10:11], v[146:147], v[90:91] op_sel:[0,1,0]
	v_pk_fma_f32 v[92:93], v[10:11], v[150:151], v[92:93] op_sel:[0,1,0]
	v_pk_fma_f32 v[94:95], v[10:11], v[154:155], v[94:95] op_sel:[0,1,0]
	v_pk_fma_f32 v[96:97], v[10:11], v[158:159], v[96:97] op_sel:[0,1,0]
	v_pk_fma_f32 v[98:99], v[10:11], v[162:163], v[98:99] op_sel:[0,1,0]
	s_waitcnt lgkmcnt(0)
	v_pk_fma_f32 v[84:85], v[14:15], v[164:165], v[84:85] op_sel_hi:[1,0,1]
	v_pk_fma_f32 v[86:87], v[14:15], v[168:169], v[86:87] op_sel_hi:[1,0,1]
	v_pk_fma_f32 v[88:89], v[14:15], v[172:173], v[88:89] op_sel_hi:[1,0,1]
	v_pk_fma_f32 v[90:91], v[14:15], v[176:177], v[90:91] op_sel_hi:[1,0,1]
	v_pk_fma_f32 v[92:93], v[14:15], v[180:181], v[92:93] op_sel_hi:[1,0,1]
	v_pk_fma_f32 v[94:95], v[14:15], v[184:185], v[94:95] op_sel_hi:[1,0,1]
	v_pk_fma_f32 v[96:97], v[14:15], v[188:189], v[96:97] op_sel_hi:[1,0,1]
	v_pk_fma_f32 v[98:99], v[14:15], v[192:193], v[98:99] op_sel_hi:[1,0,1]
	v_pk_fma_f32 v[84:85], v[4:5], v[164:165], v[84:85] op_sel:[0,1,0]
	v_pk_fma_f32 v[86:87], v[4:5], v[168:169], v[86:87] op_sel:[0,1,0]
	v_pk_fma_f32 v[88:89], v[4:5], v[172:173], v[88:89] op_sel:[0,1,0]
	v_pk_fma_f32 v[90:91], v[4:5], v[176:177], v[90:91] op_sel:[0,1,0]
	v_pk_fma_f32 v[92:93], v[4:5], v[180:181], v[92:93] op_sel:[0,1,0]
	v_pk_fma_f32 v[94:95], v[4:5], v[184:185], v[94:95] op_sel:[0,1,0]
	v_pk_fma_f32 v[96:97], v[4:5], v[188:189], v[96:97] op_sel:[0,1,0]
	v_pk_fma_f32 v[98:99], v[4:5], v[192:193], v[98:99] op_sel:[0,1,0]
	v_pk_fma_f32 v[84:85], v[38:39], v[166:167], v[84:85] op_sel_hi:[1,0,1]
	v_pk_fma_f32 v[86:87], v[38:39], v[170:171], v[86:87] op_sel_hi:[1,0,1]
	v_pk_fma_f32 v[88:89], v[38:39], v[174:175], v[88:89] op_sel_hi:[1,0,1]
	v_pk_fma_f32 v[90:91], v[38:39], v[178:179], v[90:91] op_sel_hi:[1,0,1]
	v_pk_fma_f32 v[92:93], v[38:39], v[182:183], v[92:93] op_sel_hi:[1,0,1]
	v_pk_fma_f32 v[94:95], v[38:39], v[186:187], v[94:95] op_sel_hi:[1,0,1]
	v_pk_fma_f32 v[96:97], v[38:39], v[190:191], v[96:97] op_sel_hi:[1,0,1]
	v_pk_fma_f32 v[98:99], v[38:39], v[194:195], v[98:99] op_sel_hi:[1,0,1]
	v_pk_fma_f32 v[84:85], v[6:7], v[166:167], v[84:85] op_sel:[0,1,0]
	v_pk_fma_f32 v[86:87], v[6:7], v[170:171], v[86:87] op_sel:[0,1,0]
	v_pk_fma_f32 v[88:89], v[6:7], v[174:175], v[88:89] op_sel:[0,1,0]
	v_pk_fma_f32 v[90:91], v[6:7], v[178:179], v[90:91] op_sel:[0,1,0]
	v_pk_fma_f32 v[92:93], v[6:7], v[182:183], v[92:93] op_sel:[0,1,0]
	v_pk_fma_f32 v[94:95], v[6:7], v[186:187], v[94:95] op_sel:[0,1,0]
	v_pk_fma_f32 v[96:97], v[6:7], v[190:191], v[96:97] op_sel:[0,1,0]
	v_pk_fma_f32 v[98:99], v[6:7], v[194:195], v[98:99] op_sel:[0,1,0]
	v_fma_f32 v70, v32, v44, v84
	v_fma_f32 v71, v32, v45, v85
	v_fma_f32 v68, -v34, v45, v70
	v_fma_f32 v69, v34, v44, v71
	v_fma_f32 v70, v32, v68, v86
	v_fma_f32 v71, v32, v69, v87
	v_fma_f32 v44, -v34, v69, v70
	v_fma_f32 v45, v34, v68, v71
	v_fma_f32 v70, v32, v44, v88
	v_fma_f32 v71, v32, v45, v89
	v_fma_f32 v68, -v34, v45, v70
	v_fma_f32 v69, v34, v44, v71
	v_fma_f32 v70, v32, v68, v90
	v_fma_f32 v71, v32, v69, v91
	v_fma_f32 v44, -v34, v69, v70
	v_fma_f32 v45, v34, v68, v71
	v_fma_f32 v70, v32, v44, v92
	v_fma_f32 v71, v32, v45, v93
	v_fma_f32 v68, -v34, v45, v70
	v_fma_f32 v69, v34, v44, v71
	v_fma_f32 v70, v32, v68, v94
	v_fma_f32 v71, v32, v69, v95
	v_fma_f32 v44, -v34, v69, v70
	v_fma_f32 v45, v34, v68, v71
	v_fma_f32 v70, v32, v44, v96
	v_fma_f32 v71, v32, v45, v97
	v_fma_f32 v68, -v34, v45, v70
	v_fma_f32 v69, v34, v44, v71
	v_fma_f32 v70, v32, v68, v98
	v_fma_f32 v71, v32, v69, v99
	v_fma_f32 v44, -v34, v69, v70
	v_fma_f32 v45, v34, v68, v71
	s_add_i32 s9, s9, 8
	s_cmp_ge_i32 s9, s21
	s_cbranch_scc0 .LBB0_461
	s_and_b32 s4, s30, 0x1fffffc0
	s_waitcnt vmcnt(0)
	v_or_b32_e32 v0, s4, v52
	v_lshlrev_b32_e32 v0, 3, v0
	ds_write_b64 v0, v[44:45] offset:8320

.LBB0_482:
	s_or_b64 exec, exec, s[4:5]
	s_cmp_ge_i32 s20, s21
	s_cbranch_scc1 .LBB0_500
	s_lshl_b32 s4, s8, 1
	v_readlane_b32 s5, v253, 32
	v_lshrrev_b32_e32 v35, 3, v52
	s_add_u32 s4, s5, s4
	v_readlane_b32 s5, v253, 33
	s_addc_u32 s5, s5, 0
	v_lshl_add_u32 v49, v33, 2, s31
	v_lshl_add_u32 v48, v48, 2, s31
	v_lshlrev_b32_e32 v50, 6, v47
	v_mul_u32_u24_e32 v51, 0x41, v35
	v_mul_u32_u24_e32 v56, 0x41, v33
	v_lshlrev_b32_e32 v58, 6, v35
	v_lshlrev_b32_e32 v200, 1, v33
	s_add_i32 s10, s31, 0x38c0
	s_addk_i32 s31, 0x2880
	v_or_b32_e32 v53, s34, v35
	v_lshl_add_u64 v[46:47], s[4:5], 0, v[200:201]
	v_mov_b32_e32 v33, v32
	v_mov_b32_e32 v35, v34
	v_lshl_add_u32 v54, v52, 3, s31
	v_lshl_add_u32 v55, v51, 3, s31
	v_lshlrev_b32_e32 v56, 3, v56
	v_add_u32_e32 v57, v48, v50
	v_add_u32_e32 v58, v49, v58
	v_and_b32_e32 v60, 15, v52
	v_lshrrev_b32_e32 v61, 4, v52
	v_and_b32_e32 v62, 7, v52
	v_mul_u32_u24_e32 v63, 0x208, v62
	v_lshl_add_u32 v63, v61, 2, v63
	v_add_u32_e32 v76, s31, v63
	v_mul_u32_u24_e32 v64, 0x208, v60
	v_lshl_add_u32 v64, v61, 2, v64
	v_lshlrev_b32_e32 v65, 8, v61
	v_lshl_add_u32 v65, v60, 2, v65
	v_add_u32_e32 v77, s31, v65
	v_lshrrev_b32_e32 v66, 3, v52
	v_lshlrev_b32_e32 v66, 6, v66
	v_lshl_add_u32 v66, v62, 3, v66
	v_add_u32_e32 v78, s31, v66
	v_mov_b32_e32 v79, s10
	v_lshlrev_b32_e32 v80, 31, v61
	ds_read2_b32 v[100:101], v64 offset0:0 offset1:4
	ds_read2_b32 v[102:103], v64 offset0:8 offset1:12
	ds_read2_b32 v[104:105], v64 offset0:16 offset1:20
	ds_read2_b32 v[106:107], v64 offset0:24 offset1:28
	ds_read2_b32 v[108:109], v64 offset0:32 offset1:36
	ds_read2_b32 v[110:111], v64 offset0:40 offset1:44
	ds_read2_b32 v[112:113], v64 offset0:48 offset1:52
	ds_read2_b32 v[114:115], v64 offset0:56 offset1:60
	ds_read2_b32 v[116:117], v64 offset0:64 offset1:68
	ds_read2_b32 v[118:119], v64 offset0:72 offset1:76
	ds_read2_b32 v[120:121], v64 offset0:80 offset1:84
	ds_read2_b32 v[122:123], v64 offset0:88 offset1:92
	ds_read2_b32 v[124:125], v64 offset0:96 offset1:100
	ds_read2_b32 v[126:127], v64 offset0:104 offset1:108
	ds_read2_b32 v[128:129], v64 offset0:112 offset1:116
	ds_read2_b32 v[130:131], v64 offset0:120 offset1:124
	s_waitcnt lgkmcnt(0)
	v_xor_b32_e32 v100, v80, v100
	v_xor_b32_e32 v101, v80, v101
	v_xor_b32_e32 v102, v80, v102
	v_xor_b32_e32 v103, v80, v103
	v_xor_b32_e32 v104, v80, v104
	v_xor_b32_e32 v105, v80, v105
	v_xor_b32_e32 v106, v80, v106
	v_xor_b32_e32 v107, v80, v107
	v_xor_b32_e32 v108, v80, v108
	v_xor_b32_e32 v109, v80, v109
	v_xor_b32_e32 v110, v80, v110
	v_xor_b32_e32 v111, v80, v111
	v_xor_b32_e32 v112, v80, v112
	v_xor_b32_e32 v113, v80, v113
	v_xor_b32_e32 v114, v80, v114
	v_xor_b32_e32 v115, v80, v115
	v_xor_b32_e32 v116, v80, v116
	v_xor_b32_e32 v117, v80, v117
	v_xor_b32_e32 v118, v80, v118
	v_xor_b32_e32 v119, v80, v119
	v_xor_b32_e32 v120, v80, v120
	v_xor_b32_e32 v121, v80, v121
	v_xor_b32_e32 v122, v80, v122
	v_xor_b32_e32 v123, v80, v123
	v_xor_b32_e32 v124, v80, v124
	v_xor_b32_e32 v125, v80, v125
	v_xor_b32_e32 v126, v80, v126
	v_xor_b32_e32 v127, v80, v127
	v_xor_b32_e32 v128, v80, v128
	v_xor_b32_e32 v129, v80, v129
	v_xor_b32_e32 v130, v80, v130
	v_xor_b32_e32 v131, v80, v131
	s_branch .LBB0_485

.LBB0_488:
	s_or_b64 exec, exec, s[4:5]
	s_mov_b32 s4, 0
	v_mov_b32_e32 v48, v54
	ds_read_b128 v[132:135], v79 offset:0
	ds_read_b128 v[136:139], v79 offset:64
	ds_read_b128 v[140:143], v79 offset:128
	ds_read_b128 v[144:147], v79 offset:192
	ds_read_b128 v[148:151], v79 offset:256
	ds_read_b128 v[152:155], v79 offset:320
	ds_read_b128 v[156:159], v79 offset:384
	ds_read_b128 v[160:163], v79 offset:448
	ds_read_b128 v[164:167], v79 offset:16
	ds_read_b128 v[168:171], v79 offset:80
	ds_read_b128 v[172:175], v79 offset:144
	ds_read_b128 v[176:179], v79 offset:208
	ds_read_b128 v[180:183], v79 offset:272
	ds_read_b128 v[184:187], v79 offset:336
	ds_read_b128 v[188:191], v79 offset:400
	ds_read_b128 v[192:195], v79 offset:464
	s_waitcnt lgkmcnt(8)
	v_pk_fma_f32 v[84:85], v[36:37], v[132:133], 0 op_sel_hi:[1,0,0]
	v_pk_fma_f32 v[86:87], v[36:37], v[136:137], 0 op_sel_hi:[1,0,0]
	v_pk_fma_f32 v[88:89], v[36:37], v[140:141], 0 op_sel_hi:[1,0,0]
	v_pk_fma_f32 v[90:91], v[36:37], v[144:145], 0 op_sel_hi:[1,0,0]
	v_pk_fma_f32 v[92:93], v[36:37], v[148:149], 0 op_sel_hi:[1,0,0]
	v_pk_fma_f32 v[94:95], v[36:37], v[152:153], 0 op_sel_hi:[1,0,0]
	v_pk_fma_f32 v[96:97], v[36:37], v[156:157], 0 op_sel_hi:[1,0,0]
	v_pk_fma_f32 v[98:99], v[36:37], v[160:161], 0 op_sel_hi:[1,0,0]
	v_pk_fma_f32 v[84:85], v[28:29], v[132:133], v[84:85] op_sel:[0,1,0]
	v_pk_fma_f32 v[86:87], v[28:29], v[136:137], v[86:87] op_sel:[0,1,0]
	v_pk_fma_f32 v[88:89], v[28:29], v[140:141], v[88:89] op_sel:[0,1,0]
	v_pk_fma_f32 v[90:91], v[28:29], v[144:145], v[90:91] op_sel:[0,1,0]
	v_pk_fma_f32 v[92:93], v[28:29], v[148:149], v[92:93] op_sel:[0,1,0]
	v_pk_fma_f32 v[94:95], v[28:29], v[152:153], v[94:95] op_sel:[0,1,0]
	v_pk_fma_f32 v[96:97], v[28:29], v[156:157], v[96:97] op_sel:[0,1,0]
	v_pk_fma_f32 v[98:99], v[28:29], v[160:161], v[98:99] op_sel:[0,1,0]
	v_pk_fma_f32 v[84:85], v[24:25], v[134:135], v[84:85] op_sel_hi:[1,0,1]
	v_pk_fma_f32 v[86:87], v[24:25], v[138:139], v[86:87] op_sel_hi:[1,0,1]
	v_pk_fma_f32 v[88:89], v[24:25], v[142:143], v[88:89] op_sel_hi:[1,0,1]
	v_pk_fma_f32 v[90:91], v[24:25], v[146:147], v[90:91] op_sel_hi:[1,0,1]
	v_pk_fma_f32 v[92:93], v[24:25], v[150:151], v[92:93] op_sel_hi:[1,0,1]
	v_pk_fma_f32 v[94:95], v[24:25], v[154:155], v[94:95] op_sel_hi:[1,0,1]
	v_pk_fma_f32 v[96:97], v[24:25], v[158:159], v[96:97] op_sel_hi:[1,0,1]
	v_pk_fma_f32 v[98:99], v[24:25], v[162:163], v[98:99] op_sel_hi:[1,0,1]
	v_pk_fma_f32 v[84:85], v[26:27], v[134:135], v[84:85] op_sel:[0,1,0]
	v_pk_fma_f32 v[86:87], v[26:27], v[138:139], v[86:87] op_sel:[0,1,0]
	v_pk_fma_f32 v[88:89], v[26:27], v[142:143], v[88:89] op_sel:[0,1,0]
	v_pk_fma_f32 v[90:91], v[26:27], v[146:147], v[90:91] op_sel:[0,1,0]
	v_pk_fma_f32 v[92:93], v[26:27], v[150:151], v[92:93] op_sel:[0,1,0]
	v_pk_fma_f32 v[94:95], v[26:27], v[154:155], v[94:95] op_sel:[0,1,0]
	v_pk_fma_f32 v[96:97], v[26:27], v[158:159], v[96:97] op_sel:[0,1,0]
	v_pk_fma_f32 v[98:99], v[26:27], v[162:163], v[98:99] op_sel:[0,1,0]
	ds_read_b128 v[132:135], v79 offset:32
	ds_read_b128 v[136:139], v79 offset:96
	ds_read_b128 v[140:143], v79 offset:160
	ds_read_b128 v[144:147], v79 offset:224
	ds_read_b128 v[148:151], v79 offset:288
	ds_read_b128 v[152:155], v79 offset:352
	ds_read_b128 v[156:159], v79 offset:416
	ds_read_b128 v[160:163], v79 offset:480
	s_waitcnt lgkmcnt(8)
	v_pk_fma_f32 v[84:85], v[30:31], v[164:165], v[84:85] op_sel_hi:[1,0,1]
	v_pk_fma_f32 v[86:87], v[30:31], v[168:169], v[86:87] op_sel_hi:[1,0,1]
	v_pk_fma_f32 v[88:89], v[30:31], v[172:173], v[88:89] op_sel_hi:[1,0,1]
	v_pk_fma_f32 v[90:91], v[30:31], v[176:177], v[90:91] op_sel_hi:[1,0,1]
	v_pk_fma_f32 v[92:93], v[30:31], v[180:181], v[92:93] op_sel_hi:[1,0,1]
	v_pk_fma_f32 v[94:95], v[30:31], v[184:185], v[94:95] op_sel_hi:[1,0,1]
	v_pk_fma_f32 v[96:97], v[30:31], v[188:189], v[96:97] op_sel_hi:[1,0,1]
	v_pk_fma_f32 v[98:99], v[30:31], v[192:193], v[98:99] op_sel_hi:[1,0,1]
	v_pk_fma_f32 v[84:85], v[16:17], v[164:165], v[84:85] op_sel:[0,1,0]
	v_pk_fma_f32 v[86:87], v[16:17], v[168:169], v[86:87] op_sel:[0,1,0]
	v_pk_fma_f32 v[88:89], v[16:17], v[172:173], v[88:89] op_sel:[0,1,0]
	v_pk_fma_f32 v[90:91], v[16:17], v[176:177], v[90:91] op_sel:[0,1,0]
	v_pk_fma_f32 v[92:93], v[16:17], v[180:181], v[92:93] op_sel:[0,1,0]
	v_pk_fma_f32 v[94:95], v[16:17], v[184:185], v[94:95] op_sel:[0,1,0]
	v_pk_fma_f32 v[96:97], v[16:17], v[188:189], v[96:97] op_sel:[0,1,0]
	v_pk_fma_f32 v[98:99], v[16:17], v[192:193], v[98:99] op_sel:[0,1,0]
	v_pk_fma_f32 v[84:85], v[20:21], v[166:167], v[84:85] op_sel_hi:[1,0,1]
	v_pk_fma_f32 v[86:87], v[20:21], v[170:171], v[86:87] op_sel_hi:[1,0,1]
	v_pk_fma_f32 v[88:89], v[20:21], v[174:175], v[88:89] op_sel_hi:[1,0,1]
	v_pk_fma_f32 v[90:91], v[20:21], v[178:179], v[90:91] op_sel_hi:[1,0,1]
	v_pk_fma_f32 v[92:93], v[20:21], v[182:183], v[92:93] op_sel_hi:[1,0,1]
	v_pk_fma_f32 v[94:95], v[20:21], v[186:187], v[94:95] op_sel_hi:[1,0,1]
	v_pk_fma_f32 v[96:97], v[20:21], v[190:191], v[96:97] op_sel_hi:[1,0,1]
	v_pk_fma_f32 v[98:99], v[20:21], v[194:195], v[98:99] op_sel_hi:[1,0,1]
	v_pk_fma_f32 v[84:85], v[18:19], v[166:167], v[84:85] op_sel:[0,1,0]
	v_pk_fma_f32 v[86:87], v[18:19], v[170:171], v[86:87] op_sel:[0,1,0]
	v_pk_fma_f32 v[88:89], v[18:19], v[174:175], v[88:89] op_sel:[0,1,0]
	v_pk_fma_f32 v[90:91], v[18:19], v[178:179], v[90:91] op_sel:[0,1,0]
	v_pk_fma_f32 v[92:93], v[18:19], v[182:183], v[92:93] op_sel:[0,1,0]
	v_pk_fma_f32 v[94:95], v[18:19], v[186:187], v[94:95] op_sel:[0,1,0]
	v_pk_fma_f32 v[96:97], v[18:19], v[190:191], v[96:97] op_sel:[0,1,0]
	v_pk_fma_f32 v[98:99], v[18:19], v[194:195], v[98:99] op_sel:[0,1,0]
	ds_read_b128 v[164:167], v79 offset:48
	ds_read_b128 v[168:171], v79 offset:112
	ds_read_b128 v[172:175], v79 offset:176
	ds_read_b128 v[176:179], v79 offset:240
	ds_read_b128 v[180:183], v79 offset:304
	ds_read_b128 v[184:187], v79 offset:368
	ds_read_b128 v[188:191], v79 offset:432
	ds_read_b128 v[192:195], v79 offset:496
	s_waitcnt lgkmcnt(8)
	v_pk_fma_f32 v[84:85], v[22:23], v[132:133], v[84:85] op_sel_hi:[1,0,1]
	v_pk_fma_f32 v[86:87], v[22:23], v[136:137], v[86:87] op_sel_hi:[1,0,1]
	v_pk_fma_f32 v[88:89], v[22:23], v[140:141], v[88:89] op_sel_hi:[1,0,1]
	v_pk_fma_f32 v[90:91], v[22:23], v[144:145], v[90:91] op_sel_hi:[1,0,1]
	v_pk_fma_f32 v[92:93], v[22:23], v[148:149], v[92:93] op_sel_hi:[1,0,1]
	v_pk_fma_f32 v[94:95], v[22:23], v[152:153], v[94:95] op_sel_hi:[1,0,1]
	v_pk_fma_f32 v[96:97], v[22:23], v[156:157], v[96:97] op_sel_hi:[1,0,1]
	v_pk_fma_f32 v[98:99], v[22:23], v[160:161], v[98:99] op_sel_hi:[1,0,1]
	v_pk_fma_f32 v[84:85], v[8:9], v[132:133], v[84:85] op_sel:[0,1,0]
	v_pk_fma_f32 v[86:87], v[8:9], v[136:137], v[86:87] op_sel:[0,1,0]
	v_pk_fma_f32 v[88:89], v[8:9], v[140:141], v[88:89] op_sel:[0,1,0]
	v_pk_fma_f32 v[90:91], v[8:9], v[144:145], v[90:91] op_sel:[0,1,0]
	v_pk_fma_f32 v[92:93], v[8:9], v[148:149], v[92:93] op_sel:[0,1,0]
	v_pk_fma_f32 v[94:95], v[8:9], v[152:153], v[94:95] op_sel:[0,1,0]
	v_pk_fma_f32 v[96:97], v[8:9], v[156:157], v[96:97] op_sel:[0,1,0]
	v_pk_fma_f32 v[98:99], v[8:9], v[160:161], v[98:99] op_sel:[0,1,0]
	v_pk_fma_f32 v[84:85], v[12:13], v[134:135], v[84:85] op_sel_hi:[1,0,1]
	v_pk_fma_f32 v[86:87], v[12:13], v[138:139], v[86:87] op_sel_hi:[1,0,1]
	v_pk_fma_f32 v[88:89], v[12:13], v[142:143], v[88:89] op_sel_hi:[1,0,1]
	v_pk_fma_f32 v[90:91], v[12:13], v[146:147], v[90:91] op_sel_hi:[1,0,1]
	v_pk_fma_f32 v[92:93], v[12:13], v[150:151], v[92:93] op_sel_hi:[1,0,1]
	v_pk_fma_f32 v[94:95], v[12:13], v[154:155], v[94:95] op_sel_hi:[1,0,1]
	v_pk_fma_f32 v[96:97], v[12:13], v[158:159], v[96:97] op_sel_hi:[1,0,1]
	v_pk_fma_f32 v[98:99], v[12:13], v[162:163], v[98:99] op_sel_hi:[1,0,1]
	v_pk_fma_f32 v[84:85], v[10:11], v[134:135], v[84:85] op_sel:[0,1,0]
	v_pk_fma_f32 v[86:87], v[10:11], v[138:139], v[86:87] op_sel:[0,1,0]
	v_pk_fma_f32 v[88:89], v[10:11], v[142:143], v[88:89] op_sel:[0,1,0]
	v_pk_fma_f32 v[90:91], v[10:11], v[146:147], v[90:91] op_sel:[0,1,0]
	v_pk_fma_f32 v[92:93], v[10:11], v[150:151], v[92:93] op_sel:[0,1,0]
	v_pk_fma_f32 v[94:95], v[10:11], v[154:155], v[94:95] op_sel:[0,1,0]
	v_pk_fma_f32 v[96:97], v[10:11], v[158:159], v[96:97] op_sel:[0,1,0]
	v_pk_fma_f32 v[98:99], v[10:11], v[162:163], v[98:99] op_sel:[0,1,0]
	s_waitcnt lgkmcnt(0)
	v_pk_fma_f32 v[84:85], v[14:15], v[164:165], v[84:85] op_sel_hi:[1,0,1]
	v_pk_fma_f32 v[86:87], v[14:15], v[168:169], v[86:87] op_sel_hi:[1,0,1]
	v_pk_fma_f32 v[88:89], v[14:15], v[172:173], v[88:89] op_sel_hi:[1,0,1]
	v_pk_fma_f32 v[90:91], v[14:15], v[176:177], v[90:91] op_sel_hi:[1,0,1]
	v_pk_fma_f32 v[92:93], v[14:15], v[180:181], v[92:93] op_sel_hi:[1,0,1]
	v_pk_fma_f32 v[94:95], v[14:15], v[184:185], v[94:95] op_sel_hi:[1,0,1]
	v_pk_fma_f32 v[96:97], v[14:15], v[188:189], v[96:97] op_sel_hi:[1,0,1]
	v_pk_fma_f32 v[98:99], v[14:15], v[192:193], v[98:99] op_sel_hi:[1,0,1]
	v_pk_fma_f32 v[84:85], v[4:5], v[164:165], v[84:85] op_sel:[0,1,0]
	v_pk_fma_f32 v[86:87], v[4:5], v[168:169], v[86:87] op_sel:[0,1,0]
	v_pk_fma_f32 v[88:89], v[4:5], v[172:173], v[88:89] op_sel:[0,1,0]
	v_pk_fma_f32 v[90:91], v[4:5], v[176:177], v[90:91] op_sel:[0,1,0]
	v_pk_fma_f32 v[92:93], v[4:5], v[180:181], v[92:93] op_sel:[0,1,0]
	v_pk_fma_f32 v[94:95], v[4:5], v[184:185], v[94:95] op_sel:[0,1,0]
	v_pk_fma_f32 v[96:97], v[4:5], v[188:189], v[96:97] op_sel:[0,1,0]
	v_pk_fma_f32 v[98:99], v[4:5], v[192:193], v[98:99] op_sel:[0,1,0]
	v_pk_fma_f32 v[84:85], v[38:39], v[166:167], v[84:85] op_sel_hi:[1,0,1]
	v_pk_fma_f32 v[86:87], v[38:39], v[170:171], v[86:87] op_sel_hi:[1,0,1]
	v_pk_fma_f32 v[88:89], v[38:39], v[174:175], v[88:89] op_sel_hi:[1,0,1]
	v_pk_fma_f32 v[90:91], v[38:39], v[178:179], v[90:91] op_sel_hi:[1,0,1]
	v_pk_fma_f32 v[92:93], v[38:39], v[182:183], v[92:93] op_sel_hi:[1,0,1]
	v_pk_fma_f32 v[94:95], v[38:39], v[186:187], v[94:95] op_sel_hi:[1,0,1]
	v_pk_fma_f32 v[96:97], v[38:39], v[190:191], v[96:97] op_sel_hi:[1,0,1]
	v_pk_fma_f32 v[98:99], v[38:39], v[194:195], v[98:99] op_sel_hi:[1,0,1]
	v_pk_fma_f32 v[84:85], v[6:7], v[166:167], v[84:85] op_sel:[0,1,0]
	v_pk_fma_f32 v[86:87], v[6:7], v[170:171], v[86:87] op_sel:[0,1,0]
	v_pk_fma_f32 v[88:89], v[6:7], v[174:175], v[88:89] op_sel:[0,1,0]
	v_pk_fma_f32 v[90:91], v[6:7], v[178:179], v[90:91] op_sel:[0,1,0]
	v_pk_fma_f32 v[92:93], v[6:7], v[182:183], v[92:93] op_sel:[0,1,0]
	v_pk_fma_f32 v[94:95], v[6:7], v[186:187], v[94:95] op_sel:[0,1,0]
	v_pk_fma_f32 v[96:97], v[6:7], v[190:191], v[96:97] op_sel:[0,1,0]
	v_pk_fma_f32 v[98:99], v[6:7], v[194:195], v[98:99] op_sel:[0,1,0]
	v_fma_f32 v70, v32, v44, v84
	v_fma_f32 v71, v32, v45, v85
	v_fma_f32 v68, -v34, v45, v70
	v_fma_f32 v69, v34, v44, v71
	ds_write_b64 v54, v[68:69]
	v_fma_f32 v70, v32, v68, v86
	v_fma_f32 v71, v32, v69, v87
	v_fma_f32 v44, -v34, v69, v70
	v_fma_f32 v45, v34, v68, v71
	ds_write_b64 v54, v[44:45] offset:520
	v_fma_f32 v70, v32, v44, v88
	v_fma_f32 v71, v32, v45, v89
	v_fma_f32 v68, -v34, v45, v70
	v_fma_f32 v69, v34, v44, v71
	ds_write_b64 v54, v[68:69] offset:1040
	v_fma_f32 v70, v32, v68, v90
	v_fma_f32 v71, v32, v69, v91
	v_fma_f32 v44, -v34, v69, v70
	v_fma_f32 v45, v34, v68, v71
	ds_write_b64 v54, v[44:45] offset:1560
	v_fma_f32 v70, v32, v44, v92
	v_fma_f32 v71, v32, v45, v93
	v_fma_f32 v68, -v34, v45, v70
	v_fma_f32 v69, v34, v44, v71
	ds_write_b64 v54, v[68:69] offset:2080
	v_fma_f32 v70, v32, v68, v94
	v_fma_f32 v71, v32, v69, v95
	v_fma_f32 v44, -v34, v69, v70
	v_fma_f32 v45, v34, v68, v71
	ds_write_b64 v54, v[44:45] offset:2600
	v_fma_f32 v70, v32, v44, v96
	v_fma_f32 v71, v32, v45, v97
	v_fma_f32 v68, -v34, v45, v70
	v_fma_f32 v69, v34, v44, v71
	ds_write_b64 v54, v[68:69] offset:3120
	v_fma_f32 v70, v32, v68, v98
	v_fma_f32 v71, v32, v69, v99
	v_fma_f32 v44, -v34, v69, v70
	v_fma_f32 v45, v34, v68, v71
	ds_write_b64 v54, v[44:45] offset:3640
	ds_read2_b32 v[132:133], v76 offset0:0 offset1:4
	ds_read2_b32 v[134:135], v76 offset0:8 offset1:12
	ds_read2_b32 v[136:137], v76 offset0:16 offset1:20
	ds_read2_b32 v[138:139], v76 offset0:24 offset1:28
	ds_read2_b32 v[140:141], v76 offset0:32 offset1:36
	ds_read2_b32 v[142:143], v76 offset0:40 offset1:44
	ds_read2_b32 v[144:145], v76 offset0:48 offset1:52
	ds_read2_b32 v[146:147], v76 offset0:56 offset1:60
	ds_read2_b32 v[148:149], v76 offset0:64 offset1:68
	ds_read2_b32 v[150:151], v76 offset0:72 offset1:76
	ds_read2_b32 v[152:153], v76 offset0:80 offset1:84
	ds_read2_b32 v[154:155], v76 offset0:88 offset1:92
	ds_read2_b32 v[156:157], v76 offset0:96 offset1:100
	ds_read2_b32 v[158:159], v76 offset0:104 offset1:108
	ds_read2_b32 v[160:161], v76 offset0:112 offset1:116
	ds_read2_b32 v[162:163], v76 offset0:120 offset1:124
	s_waitcnt lgkmcnt(12)
	v_mfma_f32_16x16x4_f32 v[60:63], v132, v100, 0
	v_mfma_f32_16x16x4_f32 v[64:67], v133, v101, 0
	v_mfma_f32_16x16x4_f32 v[60:63], v134, v102, v[60:63]
	v_mfma_f32_16x16x4_f32 v[64:67], v135, v103, v[64:67]
	v_mfma_f32_16x16x4_f32 v[60:63], v136, v104, v[60:63]
	v_mfma_f32_16x16x4_f32 v[64:67], v137, v105, v[64:67]
	v_mfma_f32_16x16x4_f32 v[60:63], v138, v106, v[60:63]
	v_mfma_f32_16x16x4_f32 v[64:67], v139, v107, v[64:67]
	s_waitcnt lgkmcnt(0)
	v_mfma_f32_16x16x4_f32 v[60:63], v140, v108, v[60:63]
	v_mfma_f32_16x16x4_f32 v[64:67], v141, v109, v[64:67]
	v_mfma_f32_16x16x4_f32 v[60:63], v142, v110, v[60:63]
	v_mfma_f32_16x16x4_f32 v[64:67], v143, v111, v[64:67]
	v_mfma_f32_16x16x4_f32 v[60:63], v144, v112, v[60:63]
	v_mfma_f32_16x16x4_f32 v[64:67], v145, v113, v[64:67]
	v_mfma_f32_16x16x4_f32 v[60:63], v146, v114, v[60:63]
	v_mfma_f32_16x16x4_f32 v[64:67], v147, v115, v[64:67]
	v_mfma_f32_16x16x4_f32 v[60:63], v148, v116, v[60:63]
	v_mfma_f32_16x16x4_f32 v[64:67], v149, v117, v[64:67]
	v_mfma_f32_16x16x4_f32 v[60:63], v150, v118, v[60:63]
	v_mfma_f32_16x16x4_f32 v[64:67], v151, v119, v[64:67]
	v_mfma_f32_16x16x4_f32 v[60:63], v152, v120, v[60:63]
	v_mfma_f32_16x16x4_f32 v[64:67], v153, v121, v[64:67]
	v_mfma_f32_16x16x4_f32 v[60:63], v154, v122, v[60:63]
	v_mfma_f32_16x16x4_f32 v[64:67], v155, v123, v[64:67]
	v_mfma_f32_16x16x4_f32 v[60:63], v156, v124, v[60:63]
	v_mfma_f32_16x16x4_f32 v[64:67], v157, v125, v[64:67]
	v_mfma_f32_16x16x4_f32 v[60:63], v158, v126, v[60:63]
	v_mfma_f32_16x16x4_f32 v[64:67], v159, v127, v[64:67]
	v_mfma_f32_16x16x4_f32 v[60:63], v160, v128, v[60:63]
	v_mfma_f32_16x16x4_f32 v[64:67], v161, v129, v[64:67]
	v_mfma_f32_16x16x4_f32 v[60:63], v162, v130, v[60:63]
	v_mfma_f32_16x16x4_f32 v[64:67], v163, v131, v[64:67]
	s_nop 7
	s_nop 7
	v_pk_add_f32 v[60:61], v[60:61], v[64:65]
	v_pk_add_f32 v[62:63], v[62:63], v[66:67]
	s_nop 1
	ds_write_b32 v77, v60
	ds_write_b32 v77, v61 offset:64
	ds_write_b32 v77, v62 offset:128
	ds_write_b32 v77, v63 offset:192
	ds_read_b64 v[60:61], v78
	s_waitcnt lgkmcnt(0)
	v_mov_b32_e32 v49, v60
	v_mov_b32_e32 v48, v61
	ds_read_b64 v[50:51], v58 offset:14528
	s_waitcnt vmcnt(0) lgkmcnt(0)
	v_fma_f32 v49, v42, v50, v49
	v_mul_f32_e32 v50, 0x3d372713, v49
	v_mul_f32_e32 v50, v49, v50
	v_fma_f32 v50, v49, v50, v49
	v_mul_f32_e32 v50, 0x3f4c422a, v50
	v_cmp_nlt_f32_e64 s[4:5], |v50|, s24
	s_and_saveexec_b64 s[8:9], s[4:5]
	s_xor_b64 s[4:5], exec, s[8:9]
	s_cbranch_execz .LBB0_494
	v_add_f32_e64 v59, |v50|, |v50|
	v_mul_f32_e32 v60, 0x3fb8aa3b, v59
	v_rndne_f32_e32 v61, v60
	s_mov_b32 s8, 0x3fb8aa3b
	v_sub_f32_e32 v62, v60, v61
	v_fma_f32 v60, v59, s8, -v60
	v_fmac_f32_e32 v60, 0x32a5705f, v59
	v_add_f32_e32 v60, v62, v60
	v_cvt_i32_f32_e32 v61, v61
	v_exp_f32_e32 v60, v60
	s_mov_b32 s8, 0xc2ce8ed0
	v_cmp_ngt_f32_e64 s[8:9], s8, v59
	v_ldexp_f32 v60, v60, v61
	s_nop 0
	v_cndmask_b32_e64 v60, 0, v60, s[8:9]
	s_mov_b32 s8, 0x42b17218
	v_cmp_nlt_f32_e64 s[8:9], s8, v59
	s_nop 1
	v_cndmask_b32_e64 v59, v233, v60, s[8:9]
	v_add_f32_e32 v59, 1.0, v59
	v_rcp_f32_e32 v59, v59
	s_nop 0
	v_fma_f32 v59, v59, -2.0, 1.0
